# K-loop first iteration peeled (GU and WIN copies): first MFMA of every accumulator quad takes SrcC=0, the 128-register zeroing block is deleted
# speedup vs baseline: 1.0079x; 1.0059x over previous
; #define PG8_STAGE(bufoff, gbase, voff) do { _Pragma("unroll") for (int _i = 0; _i < 2; ++_i) \
;         __builtin_amdgcn_global_load_lds((const unsigned*)((const char*)(gbase) + (voff)[_i]), (PG8_LAS unsigned*)(lds + (bufoff) + ldsw + _i * 8192), 16, 0, 0); } while (0)
; #define PG8_LDA(dst, b, h) do { _Pragma("unroll") for (int m = 0; m < 4; ++m) _Pragma("unroll") for (int k = 0; k < 2; ++k) dst[m][k] = *(const PG8_LAS bf16x8*)(lds + PG8_SA(b, h) + aoff + m * 2048 + k * 1024); } while (0)
; #define PG8_LDB(dst, b, h) do { _Pragma("unroll") for (int n = 0; n < 2; ++n) _Pragma("unroll") for (int k = 0; k < 2; ++k) dst[n][k] = *(const PG8_LAS bf16x8*)(lds + PG8_SB(b, h) + boff + n * 2048 + k * 1024); } while (0)
; #define PG8_MMA(ai, bj, At, Bt) do { __builtin_amdgcn_s_setprio(1); _Pragma("unroll") for (int m = 0; m < 4; ++m) _Pragma("unroll") for (int n = 0; n < 2; ++n) _Pragma("unroll") for (int k = 0; k < 2; ++k) \
;         acc[ai][bj][m][n] = __builtin_amdgcn_mfma_f32_16x16x32_bf16(Bt[n][k], At[m][k], acc[ai][bj][m][n], 0, 0, 0); __builtin_amdgcn_s_setprio(0); } while (0)
; #define PG8_WAIT_V(n) asm volatile("s_waitcnt vmcnt(" #n ")" ::: "memory")
; #define PG8_BAR __builtin_amdgcn_s_barrier()
; template <class Epi, class Sched, bool ALIGN_EPI = false, bool SP2 = false>
; __device__ __forceinline__ void gemm_phase(PG8_LAS unsigned char* lds, const Gemm g, const Sched& S, const Epi& E, const int wave_s) {
;     ...
;         const char* nA = has_next ? (const char*)g.A + (size_t)nxt.pm * tstep + (size_t)nxt.k0 * kstep : cA; const char* nB = has_next ? (const char*)g.Bt + (size_t)nxt.pn * tstep + (size_t)nxt.k0 * kstep : cB;
;         const int clen = cur.len;
;         for (int t = 0; t < clen; t += 2) {
;             const bool last = (t == clen - 2);
;             const char* a1 = cA + (size_t)(t + 1) * kstep;
;             const char* a2 = last ? nA : cA + (size_t)(t + 2) * kstep; const char* b2 = last ? nB : cB + (size_t)(t + 2) * kstep;
;             const char* a3 = a2 + kstep; const char* b3 = b2 + kstep;
;             if (last && has_next) S.a_ready(nxt);
;             if constexpr (SP2) {
;             PG8_LDB(B0, 0, 0); PG8_LDB(B1, 0, 1); PG8_SCHED; PG8_LDA(At, 0, 0); PG8_STAGE(PG8_SA(1, 1), a1 + hstep, voffA);
;             PG8_WAIT_V(8); PG8_WAIT_L(0); PG8_BAR; PG8_MMA(0, 0, At, B0); PG8_MMA(0, 1, At, B1); PG8_BAR; PG8_SCHED;
.LBB0_300:
	s_ashr_i32 s25, s24, 31
	s_lshl_b64 s[26:27], s[24:25], 19
	s_add_u32 s26, s38, s26
	s_addc_u32 s27, s39, s27
	s_and_b64 s[28:29], s[6:7], exec
	s_cselect_b32 s9, s27, s35
	s_cselect_b32 s25, s26, s34
	s_ashr_i32 s23, s22, 31
	s_lshl_b64 s[28:29], s[22:23], 19
	s_add_u32 s28, s40, s28
	s_addc_u32 s29, s41, s29
	s_and_b64 s[36:37], s[6:7], exec
	s_cselect_b32 s23, s29, s3
	s_cselect_b32 s31, s28, s2
	s_add_u32 s34, s34, 0x40080
	s_addc_u32 s35, s35, 0
	s_add_u32 s52, s2, 0x100
	s_addc_u32 s53, s3, 0
	s_mov_b32 s54, -2
	s_add_u32 s2, s34, 0xfffc0080
	s_addc_u32 s3, s35, -1
	s_add_i32 s55, 0, 0x10000
	s_cmp_eq_u32 s54, 12
	s_cselect_b32 s37, s9, s3
	s_cselect_b32 s36, s25, s2
	s_cselect_b32 s3, s23, s53
	s_cselect_b32 s2, s31, s52
	s_add_i32 s58, 0, 0x14000
	v_add_u32_e32 v156, s55, v146
	v_add_u32_e32 v160, s58, v146
	ds_read_b128 v[140:143], v156
	ds_read_b128 v[148:151], v156 offset:1024
	ds_read_b128 v[152:155], v156 offset:2048
	ds_read_b128 v[156:159], v156 offset:3072
	ds_read_b128 v[174:177], v160
	ds_read_b128 v[178:181], v160 offset:1024
	ds_read_b128 v[182:185], v160 offset:2048
	ds_read_b128 v[186:189], v160 offset:3072
	v_lshl_add_u64 v[160:161], s[34:35], 0, v[136:137]
	s_add_i32 m0, s43, 0xc000
	ds_read_b128 v[190:193], v147
	ds_read_b128 v[210:213], v147 offset:1024
	ds_read_b128 v[214:217], v147 offset:2048
	ds_read_b128 v[218:221], v147 offset:3072
	ds_read_b128 v[222:225], v147 offset:4096
	ds_read_b128 v[226:229], v147 offset:5120
	ds_read_b128 v[230:233], v147 offset:6144
	ds_read_b128 v[234:237], v147 offset:7168
	global_load_lds_dwordx4 v[160:161], off
	v_lshl_add_u64 v[160:161], s[34:35], 0, v[138:139]
	s_add_i32 m0, s43, 0xe000
	s_nop 0
	global_load_lds_dwordx4 v[160:161], off
	s_waitcnt vmcnt(8)
	s_waitcnt lgkmcnt(0)
	s_barrier
	s_setprio 1
	s_waitcnt lgkmcnt(0)
	v_mfma_f32_16x16x32_bf16 v[124:127], v[140:143], v[190:193], 0
	v_mfma_f32_16x16x32_bf16 v[120:123], v[152:155], v[190:193], 0
	v_mfma_f32_16x16x32_bf16 v[108:111], v[140:143], v[214:217], 0
	v_mfma_f32_16x16x32_bf16 v[104:107], v[152:155], v[214:217], 0
	v_mfma_f32_16x16x32_bf16 v[92:95], v[140:143], v[222:225], 0
	v_mfma_f32_16x16x32_bf16 v[88:91], v[152:155], v[222:225], 0
	v_mfma_f32_16x16x32_bf16 v[76:79], v[140:143], v[230:233], 0
	v_mfma_f32_16x16x32_bf16 v[72:75], v[152:155], v[230:233], 0
	v_mfma_f32_16x16x32_bf16 v[124:127], v[148:151], v[210:213], v[124:127]
	v_mfma_f32_16x16x32_bf16 v[120:123], v[156:159], v[210:213], v[120:123]
	v_mfma_f32_16x16x32_bf16 v[108:111], v[148:151], v[218:221], v[108:111]
	v_mfma_f32_16x16x32_bf16 v[104:107], v[156:159], v[218:221], v[104:107]
	v_mfma_f32_16x16x32_bf16 v[92:95], v[148:151], v[226:229], v[92:95]
	v_mfma_f32_16x16x32_bf16 v[88:91], v[156:159], v[226:229], v[88:91]
	v_mfma_f32_16x16x32_bf16 v[76:79], v[148:151], v[234:237], v[76:79]
	v_mfma_f32_16x16x32_bf16 v[72:75], v[156:159], v[234:237], v[72:75]
	s_setprio 0
	s_setprio 1
	v_mfma_f32_16x16x32_bf16 v[116:119], v[174:177], v[190:193], 0
	v_mfma_f32_16x16x32_bf16 v[112:115], v[182:185], v[190:193], 0
	v_mfma_f32_16x16x32_bf16 v[100:103], v[174:177], v[214:217], 0
	v_mfma_f32_16x16x32_bf16 v[96:99], v[182:185], v[214:217], 0
	v_mfma_f32_16x16x32_bf16 v[84:87], v[174:177], v[222:225], 0
	v_mfma_f32_16x16x32_bf16 v[80:83], v[182:185], v[222:225], 0
	v_mfma_f32_16x16x32_bf16 v[68:71], v[174:177], v[230:233], 0
	v_mfma_f32_16x16x32_bf16 v[64:67], v[182:185], v[230:233], 0
	v_mfma_f32_16x16x32_bf16 v[116:119], v[178:181], v[210:213], v[116:119]
	v_mfma_f32_16x16x32_bf16 v[112:115], v[186:189], v[210:213], v[112:115]
	v_mfma_f32_16x16x32_bf16 v[100:103], v[178:181], v[218:221], v[100:103]
	v_mfma_f32_16x16x32_bf16 v[96:99], v[186:189], v[218:221], v[96:99]
	v_mfma_f32_16x16x32_bf16 v[84:87], v[178:181], v[226:229], v[84:87]
	v_mfma_f32_16x16x32_bf16 v[80:83], v[186:189], v[226:229], v[80:83]
	v_mfma_f32_16x16x32_bf16 v[68:71], v[178:181], v[234:237], v[68:71]
	v_mfma_f32_16x16x32_bf16 v[64:67], v[186:189], v[234:237], v[64:67]
	s_setprio 0
	s_barrier
; #define PG8_STAGE(bufoff, gbase, voff) do { _Pragma("unroll") for (int _i = 0; _i < 2; ++_i) \
;         __builtin_amdgcn_global_load_lds((const unsigned*)((const char*)(gbase) + (voff)[_i]), (PG8_LAS unsigned*)(lds + (bufoff) + ldsw + _i * 8192), 16, 0, 0); } while (0)
; #define PG8_LDA(dst, b, h) do { _Pragma("unroll") for (int m = 0; m < 4; ++m) _Pragma("unroll") for (int k = 0; k < 2; ++k) dst[m][k] = *(const PG8_LAS bf16x8*)(lds + PG8_SA(b, h) + aoff + m * 2048 + k * 1024); } while (0)
; #define PG8_MMA(ai, bj, At, Bt) do { __builtin_amdgcn_s_setprio(1); _Pragma("unroll") for (int m = 0; m < 4; ++m) _Pragma("unroll") for (int n = 0; n < 2; ++n) _Pragma("unroll") for (int k = 0; k < 2; ++k) \
;         acc[ai][bj][m][n] = __builtin_amdgcn_mfma_f32_16x16x32_bf16(Bt[n][k], At[m][k], acc[ai][bj][m][n], 0, 0, 0); __builtin_amdgcn_s_setprio(0); } while (0)
; #define PG8_WAIT_V(n) asm volatile("s_waitcnt vmcnt(" #n ")" ::: "memory")
; #define PG8_WAIT_L(n) asm volatile("s_waitcnt lgkmcnt(" #n ")" ::: "memory")
; #define PG8_BAR __builtin_amdgcn_s_barrier()
; #define PG8_SCHED __builtin_amdgcn_sched_barrier(0)
; template <class Epi, class Sched, bool ALIGN_EPI = false, bool SP2 = false>
; __device__ __forceinline__ void gemm_phase(PG8_LAS unsigned char* lds, const Gemm g, const Sched& S, const Epi& E, const int wave_s) {
;     ...
;             PG8_LDA(At, 0, 1); PG8_STAGE(PG8_SB(0, 0), b2, voffB); PG8_STAGE(PG8_SB(0, 1), b2 + hstep, voffB); PG8_STAGE(PG8_SA(0, 0), a2, voffA);
;             PG8_WAIT_V(8); PG8_WAIT_L(0); PG8_BAR; PG8_MMA(1, 0, At, B0); PG8_MMA(1, 1, At, B1); PG8_BAR; PG8_SCHED;
	s_add_i32 s55, s55, s42
	v_lshl_add_u64 v[160:161], s[2:3], 0, v[128:129]
	s_mov_b32 m0, s55
	ds_read_b128 v[190:193], v147 offset:16384
	ds_read_b128 v[210:213], v147 offset:17408
	ds_read_b128 v[214:217], v147 offset:18432
	ds_read_b128 v[218:221], v147 offset:19456
	ds_read_b128 v[222:225], v147 offset:20480
	ds_read_b128 v[226:229], v147 offset:21504
	ds_read_b128 v[230:233], v147 offset:22528
	ds_read_b128 v[234:237], v147 offset:23552
	global_load_lds_dwordx4 v[160:161], off
	s_add_i32 m0, s55, 0x2000
	s_add_u32 s56, s2, 0x40000
	v_lshl_add_u64 v[194:195], s[2:3], 0, v[134:135]
	s_addc_u32 s57, s3, 0
	s_add_i32 s55, s58, s42
	global_load_lds_dwordx4 v[194:195], off
	v_lshl_add_u64 v[206:207], s[56:57], 0, v[128:129]
	s_mov_b32 m0, s55
	v_lshl_add_u64 v[238:239], s[36:37], 0, v[132:133]
	global_load_lds_dwordx4 v[206:207], off
	v_lshl_add_u64 v[206:207], s[56:57], 0, v[134:135]
	s_add_i32 m0, s55, 0x2000
	s_nop 0
	global_load_lds_dwordx4 v[206:207], off
	v_lshl_add_u64 v[206:207], s[36:37], 0, v[130:131]
	s_mov_b32 m0, s43
	s_nop 0
	global_load_lds_dwordx4 v[206:207], off
	s_mov_b32 m0, s44
	s_nop 0
	global_load_lds_dwordx4 v[238:239], off
	s_waitcnt vmcnt(8)
	s_waitcnt lgkmcnt(0)
	s_barrier
	s_setprio 1
	s_waitcnt lgkmcnt(0)
	v_mfma_f32_16x16x32_bf16 v[60:63], v[140:143], v[190:193], 0
	v_mfma_f32_16x16x32_bf16 v[56:59], v[152:155], v[190:193], 0
	v_mfma_f32_16x16x32_bf16 v[44:47], v[140:143], v[214:217], 0
	v_mfma_f32_16x16x32_bf16 v[40:43], v[152:155], v[214:217], 0
	v_mfma_f32_16x16x32_bf16 v[28:31], v[140:143], v[222:225], 0
	v_mfma_f32_16x16x32_bf16 v[24:27], v[152:155], v[222:225], 0
	v_mfma_f32_16x16x32_bf16 v[12:15], v[140:143], v[230:233], 0
	v_mfma_f32_16x16x32_bf16 v[8:11], v[152:155], v[230:233], 0
	v_mfma_f32_16x16x32_bf16 v[60:63], v[148:151], v[210:213], v[60:63]
	v_mfma_f32_16x16x32_bf16 v[56:59], v[156:159], v[210:213], v[56:59]
	v_mfma_f32_16x16x32_bf16 v[44:47], v[148:151], v[218:221], v[44:47]
	v_mfma_f32_16x16x32_bf16 v[40:43], v[156:159], v[218:221], v[40:43]
	v_mfma_f32_16x16x32_bf16 v[28:31], v[148:151], v[226:229], v[28:31]
	v_mfma_f32_16x16x32_bf16 v[24:27], v[156:159], v[226:229], v[24:27]
	v_mfma_f32_16x16x32_bf16 v[12:15], v[148:151], v[234:237], v[12:15]
	v_mfma_f32_16x16x32_bf16 v[8:11], v[156:159], v[234:237], v[8:11]
	s_setprio 0
	s_setprio 1
	v_mfma_f32_16x16x32_bf16 v[52:55], v[174:177], v[190:193], 0
	v_mfma_f32_16x16x32_bf16 v[48:51], v[182:185], v[190:193], 0
	v_mfma_f32_16x16x32_bf16 v[36:39], v[174:177], v[214:217], 0
	v_mfma_f32_16x16x32_bf16 v[32:35], v[182:185], v[214:217], 0
	v_mfma_f32_16x16x32_bf16 v[20:23], v[174:177], v[222:225], 0
	v_mfma_f32_16x16x32_bf16 v[16:19], v[182:185], v[222:225], 0
	v_mfma_f32_16x16x32_bf16 v[4:7], v[174:177], v[230:233], 0
	v_mfma_f32_16x16x32_bf16 v[0:3], v[182:185], v[230:233], 0
	v_mfma_f32_16x16x32_bf16 v[52:55], v[178:181], v[210:213], v[52:55]
	v_mfma_f32_16x16x32_bf16 v[48:51], v[186:189], v[210:213], v[48:51]
	v_mfma_f32_16x16x32_bf16 v[36:39], v[178:181], v[218:221], v[36:39]
	v_mfma_f32_16x16x32_bf16 v[32:35], v[186:189], v[218:221], v[32:35]
	v_mfma_f32_16x16x32_bf16 v[20:23], v[178:181], v[226:229], v[20:23]
	v_mfma_f32_16x16x32_bf16 v[16:19], v[186:189], v[226:229], v[16:19]
	v_mfma_f32_16x16x32_bf16 v[4:7], v[178:181], v[234:237], v[4:7]
	v_mfma_f32_16x16x32_bf16 v[0:3], v[186:189], v[234:237], v[0:3]
	s_setprio 0
	s_barrier
	s_branch .Lpeel0_seg3

; #define PG8_STAGE(bufoff, gbase, voff) do { _Pragma("unroll") for (int _i = 0; _i < 2; ++_i) \
;         __builtin_amdgcn_global_load_lds((const unsigned*)((const char*)(gbase) + (voff)[_i]), (PG8_LAS unsigned*)(lds + (bufoff) + ldsw + _i * 8192), 16, 0, 0); } while (0)
; #define PG8_LDA(dst, b, h) do { _Pragma("unroll") for (int m = 0; m < 4; ++m) _Pragma("unroll") for (int k = 0; k < 2; ++k) dst[m][k] = *(const PG8_LAS bf16x8*)(lds + PG8_SA(b, h) + aoff + m * 2048 + k * 1024); } while (0)
; #define PG8_LDB(dst, b, h) do { _Pragma("unroll") for (int n = 0; n < 2; ++n) _Pragma("unroll") for (int k = 0; k < 2; ++k) dst[n][k] = *(const PG8_LAS bf16x8*)(lds + PG8_SB(b, h) + boff + n * 2048 + k * 1024); } while (0)
; #define PG8_MMA(ai, bj, At, Bt) do { __builtin_amdgcn_s_setprio(1); _Pragma("unroll") for (int m = 0; m < 4; ++m) _Pragma("unroll") for (int n = 0; n < 2; ++n) _Pragma("unroll") for (int k = 0; k < 2; ++k) \
;         acc[ai][bj][m][n] = __builtin_amdgcn_mfma_f32_16x16x32_bf16(Bt[n][k], At[m][k], acc[ai][bj][m][n], 0, 0, 0); __builtin_amdgcn_s_setprio(0); } while (0)
; #define PG8_WAIT_V(n) asm volatile("s_waitcnt vmcnt(" #n ")" ::: "memory")
; #define PG8_WAIT_L(n) asm volatile("s_waitcnt lgkmcnt(" #n ")" ::: "memory")
; #define PG8_BAR __builtin_amdgcn_s_barrier()
; #define PG8_SCHED __builtin_amdgcn_sched_barrier(0)
; template <class Epi, class Sched, bool ALIGN_EPI = false, bool SP2 = false>
; __device__ __forceinline__ void gemm_phase(PG8_LAS unsigned char* lds, const Gemm g, const Sched& S, const Epi& E, const int wave_s) {
;     ...
;             PG8_LDB(B0, 1, 0); PG8_LDB(B1, 1, 1); PG8_SCHED; PG8_LDA(At, 1, 0); PG8_STAGE(PG8_SA(0, 1), a2 + hstep, voffA);
;             PG8_WAIT_V(8); PG8_WAIT_L(0); PG8_BAR; PG8_MMA(0, 0, At, B0); PG8_MMA(0, 1, At, B1); PG8_BAR; PG8_SCHED;
.Lpeel0_seg3:
	s_add_i32 s55, 0, 0x18000
	s_add_i32 s56, 0, 0x1c000
	v_add_u32_e32 v156, s55, v146
	v_add_u32_e32 v171, s56, v146
	ds_read_b128 v[140:143], v156
	ds_read_b128 v[148:151], v156 offset:1024
	ds_read_b128 v[152:155], v156 offset:2048
	ds_read_b128 v[156:159], v156 offset:3072
	ds_read_b128 v[174:177], v171
	ds_read_b128 v[178:181], v171 offset:1024
	ds_read_b128 v[182:185], v171 offset:2048
	ds_read_b128 v[186:189], v171 offset:3072
	s_add_u32 s36, s36, 0x40000
	s_addc_u32 s37, s37, 0
	s_mov_b32 m0, s45
	v_lshl_add_u64 v[240:241], s[36:37], 0, v[130:131]
	ds_read_b128 v[190:193], v147 offset:32768
	ds_read_b128 v[210:213], v147 offset:33792
	ds_read_b128 v[214:217], v147 offset:34816
	ds_read_b128 v[218:221], v147 offset:35840
	ds_read_b128 v[222:225], v147 offset:36864
	ds_read_b128 v[226:229], v147 offset:37888
	ds_read_b128 v[230:233], v147 offset:38912
	ds_read_b128 v[234:237], v147 offset:39936
	global_load_lds_dwordx4 v[240:241], off
	v_lshl_add_u64 v[240:241], s[36:37], 0, v[132:133]
	s_mov_b32 m0, s46
	s_nop 0
	global_load_lds_dwordx4 v[240:241], off
	s_waitcnt vmcnt(8)
	s_waitcnt lgkmcnt(0)
	s_barrier
	s_setprio 1
	s_waitcnt lgkmcnt(0)
	v_mfma_f32_16x16x32_bf16 v[124:127], v[140:143], v[190:193], v[124:127]
	v_mfma_f32_16x16x32_bf16 v[120:123], v[152:155], v[190:193], v[120:123]
	v_mfma_f32_16x16x32_bf16 v[108:111], v[140:143], v[214:217], v[108:111]
	v_mfma_f32_16x16x32_bf16 v[104:107], v[152:155], v[214:217], v[104:107]
	v_mfma_f32_16x16x32_bf16 v[92:95], v[140:143], v[222:225], v[92:95]
	v_mfma_f32_16x16x32_bf16 v[88:91], v[152:155], v[222:225], v[88:91]
	v_mfma_f32_16x16x32_bf16 v[76:79], v[140:143], v[230:233], v[76:79]
	v_mfma_f32_16x16x32_bf16 v[72:75], v[152:155], v[230:233], v[72:75]
	v_mfma_f32_16x16x32_bf16 v[124:127], v[148:151], v[210:213], v[124:127]
	v_mfma_f32_16x16x32_bf16 v[120:123], v[156:159], v[210:213], v[120:123]
	v_mfma_f32_16x16x32_bf16 v[108:111], v[148:151], v[218:221], v[108:111]
	v_mfma_f32_16x16x32_bf16 v[104:107], v[156:159], v[218:221], v[104:107]
	v_mfma_f32_16x16x32_bf16 v[92:95], v[148:151], v[226:229], v[92:95]
	v_mfma_f32_16x16x32_bf16 v[88:91], v[156:159], v[226:229], v[88:91]
	v_mfma_f32_16x16x32_bf16 v[76:79], v[148:151], v[234:237], v[76:79]
	v_mfma_f32_16x16x32_bf16 v[72:75], v[156:159], v[234:237], v[72:75]
	s_setprio 0
	s_setprio 1
	v_mfma_f32_16x16x32_bf16 v[116:119], v[174:177], v[190:193], v[116:119]
	v_mfma_f32_16x16x32_bf16 v[112:115], v[182:185], v[190:193], v[112:115]
	v_mfma_f32_16x16x32_bf16 v[100:103], v[174:177], v[214:217], v[100:103]
	v_mfma_f32_16x16x32_bf16 v[96:99], v[182:185], v[214:217], v[96:99]
	v_mfma_f32_16x16x32_bf16 v[84:87], v[174:177], v[222:225], v[84:87]
	v_mfma_f32_16x16x32_bf16 v[80:83], v[182:185], v[222:225], v[80:83]
	v_mfma_f32_16x16x32_bf16 v[68:71], v[174:177], v[230:233], v[68:71]
	v_mfma_f32_16x16x32_bf16 v[64:67], v[182:185], v[230:233], v[64:67]
	v_mfma_f32_16x16x32_bf16 v[116:119], v[178:181], v[210:213], v[116:119]
	v_mfma_f32_16x16x32_bf16 v[112:115], v[186:189], v[210:213], v[112:115]
	v_mfma_f32_16x16x32_bf16 v[100:103], v[178:181], v[218:221], v[100:103]
	v_mfma_f32_16x16x32_bf16 v[96:99], v[186:189], v[218:221], v[96:99]
	v_mfma_f32_16x16x32_bf16 v[84:87], v[178:181], v[226:229], v[84:87]
	v_mfma_f32_16x16x32_bf16 v[80:83], v[186:189], v[226:229], v[80:83]
	v_mfma_f32_16x16x32_bf16 v[68:71], v[178:181], v[234:237], v[68:71]
	v_mfma_f32_16x16x32_bf16 v[64:67], v[186:189], v[234:237], v[64:67]
	s_setprio 0
	s_barrier
; #define PG8_STAGE(bufoff, gbase, voff) do { _Pragma("unroll") for (int _i = 0; _i < 2; ++_i) \
;         __builtin_amdgcn_global_load_lds((const unsigned*)((const char*)(gbase) + (voff)[_i]), (PG8_LAS unsigned*)(lds + (bufoff) + ldsw + _i * 8192), 16, 0, 0); } while (0)
; #define PG8_LDA(dst, b, h) do { _Pragma("unroll") for (int m = 0; m < 4; ++m) _Pragma("unroll") for (int k = 0; k < 2; ++k) dst[m][k] = *(const PG8_LAS bf16x8*)(lds + PG8_SA(b, h) + aoff + m * 2048 + k * 1024); } while (0)
; #define PG8_MMA(ai, bj, At, Bt) do { __builtin_amdgcn_s_setprio(1); _Pragma("unroll") for (int m = 0; m < 4; ++m) _Pragma("unroll") for (int n = 0; n < 2; ++n) _Pragma("unroll") for (int k = 0; k < 2; ++k) \
;         acc[ai][bj][m][n] = __builtin_amdgcn_mfma_f32_16x16x32_bf16(Bt[n][k], At[m][k], acc[ai][bj][m][n], 0, 0, 0); __builtin_amdgcn_s_setprio(0); } while (0)
; #define PG8_WAIT_V(n) asm volatile("s_waitcnt vmcnt(" #n ")" ::: "memory")
; #define PG8_WAIT_L(n) asm volatile("s_waitcnt lgkmcnt(" #n ")" ::: "memory")
; #define PG8_BAR __builtin_amdgcn_s_barrier()
; #define PG8_SCHED __builtin_amdgcn_sched_barrier(0)
; template <class Epi, class Sched, bool ALIGN_EPI = false, bool SP2 = false>
; __device__ __forceinline__ void gemm_phase(PG8_LAS unsigned char* lds, const Gemm g, const Sched& S, const Epi& E, const int wave_s) {
;     ...
;         for (int t = 0; t < clen; t += 2) {
;     ...
;             PG8_LDA(At, 1, 1); PG8_STAGE(PG8_SB(1, 0), b3, voffB); PG8_STAGE(PG8_SB(1, 1), b3 + hstep, voffB); PG8_STAGE(PG8_SA(1, 0), a3, voffA);
;             PG8_WAIT_V(8); PG8_WAIT_L(0); PG8_BAR; PG8_MMA(1, 0, At, B0); PG8_MMA(1, 1, At, B1); PG8_BAR; PG8_SCHED;
	s_add_i32 s36, s55, s42
	v_lshl_add_u64 v[160:161], v[160:161], 0, s[4:5]
	s_mov_b32 m0, s36
	ds_read_b128 v[190:193], v147 offset:49152
	ds_read_b128 v[210:213], v147 offset:50176
	ds_read_b128 v[214:217], v147 offset:51200
	ds_read_b128 v[218:221], v147 offset:52224
	ds_read_b128 v[222:225], v147 offset:53248
	ds_read_b128 v[226:229], v147 offset:54272
	ds_read_b128 v[230:233], v147 offset:55296
	ds_read_b128 v[234:237], v147 offset:56320
	global_load_lds_dwordx4 v[160:161], off
	s_add_i32 m0, s36, 0x2000
	s_add_u32 s2, s2, 0x40080
	v_lshl_add_u64 v[160:161], v[194:195], 0, s[4:5]
	s_addc_u32 s3, s3, 0
	s_add_i32 s36, s56, s42
	global_load_lds_dwordx4 v[160:161], off
	v_lshl_add_u64 v[160:161], s[2:3], 0, v[128:129]
	s_mov_b32 m0, s36
	s_nop 0
	global_load_lds_dwordx4 v[160:161], off
	v_lshl_add_u64 v[160:161], s[2:3], 0, v[134:135]
	s_add_i32 m0, s36, 0x2000
	s_nop 0
	global_load_lds_dwordx4 v[160:161], off
	v_lshl_add_u64 v[160:161], v[206:207], 0, s[4:5]
	s_mov_b32 m0, s49
	s_nop 0
	global_load_lds_dwordx4 v[160:161], off
	v_lshl_add_u64 v[160:161], v[238:239], 0, s[4:5]
	s_mov_b32 m0, s50
	s_nop 0
	global_load_lds_dwordx4 v[160:161], off
	s_waitcnt vmcnt(8)
	s_waitcnt lgkmcnt(0)
	s_barrier
	s_setprio 1
	s_waitcnt lgkmcnt(0)
	v_mfma_f32_16x16x32_bf16 v[60:63], v[140:143], v[190:193], v[60:63]
	v_mfma_f32_16x16x32_bf16 v[56:59], v[152:155], v[190:193], v[56:59]
	v_mfma_f32_16x16x32_bf16 v[44:47], v[140:143], v[214:217], v[44:47]
	v_mfma_f32_16x16x32_bf16 v[40:43], v[152:155], v[214:217], v[40:43]
	v_mfma_f32_16x16x32_bf16 v[28:31], v[140:143], v[222:225], v[28:31]
	v_mfma_f32_16x16x32_bf16 v[24:27], v[152:155], v[222:225], v[24:27]
	v_mfma_f32_16x16x32_bf16 v[12:15], v[140:143], v[230:233], v[12:15]
	v_mfma_f32_16x16x32_bf16 v[8:11], v[152:155], v[230:233], v[8:11]
	v_mfma_f32_16x16x32_bf16 v[60:63], v[148:151], v[210:213], v[60:63]
	v_mfma_f32_16x16x32_bf16 v[56:59], v[156:159], v[210:213], v[56:59]
	v_mfma_f32_16x16x32_bf16 v[44:47], v[148:151], v[218:221], v[44:47]
	v_mfma_f32_16x16x32_bf16 v[40:43], v[156:159], v[218:221], v[40:43]
	v_mfma_f32_16x16x32_bf16 v[28:31], v[148:151], v[226:229], v[28:31]
	v_mfma_f32_16x16x32_bf16 v[24:27], v[156:159], v[226:229], v[24:27]
	v_mfma_f32_16x16x32_bf16 v[12:15], v[148:151], v[234:237], v[12:15]
	v_mfma_f32_16x16x32_bf16 v[8:11], v[156:159], v[234:237], v[8:11]
	s_setprio 0
	s_setprio 1
	v_mfma_f32_16x16x32_bf16 v[52:55], v[174:177], v[190:193], v[52:55]
	v_mfma_f32_16x16x32_bf16 v[48:51], v[182:185], v[190:193], v[48:51]
	v_mfma_f32_16x16x32_bf16 v[36:39], v[174:177], v[214:217], v[36:39]
	v_mfma_f32_16x16x32_bf16 v[32:35], v[182:185], v[214:217], v[32:35]
	v_mfma_f32_16x16x32_bf16 v[20:23], v[174:177], v[222:225], v[20:23]
	v_mfma_f32_16x16x32_bf16 v[16:19], v[182:185], v[222:225], v[16:19]
	v_mfma_f32_16x16x32_bf16 v[4:7], v[174:177], v[230:233], v[4:7]
	v_mfma_f32_16x16x32_bf16 v[0:3], v[182:185], v[230:233], v[0:3]
	v_mfma_f32_16x16x32_bf16 v[52:55], v[178:181], v[210:213], v[52:55]
	v_mfma_f32_16x16x32_bf16 v[48:51], v[186:189], v[210:213], v[48:51]
	v_mfma_f32_16x16x32_bf16 v[36:39], v[178:181], v[218:221], v[36:39]
	v_mfma_f32_16x16x32_bf16 v[32:35], v[186:189], v[218:221], v[32:35]
	v_mfma_f32_16x16x32_bf16 v[20:23], v[178:181], v[226:229], v[20:23]
	v_mfma_f32_16x16x32_bf16 v[16:19], v[186:189], v[226:229], v[16:19]
	v_mfma_f32_16x16x32_bf16 v[4:7], v[178:181], v[234:237], v[4:7]
	v_mfma_f32_16x16x32_bf16 v[0:3], v[186:189], v[234:237], v[0:3]
	s_setprio 0
	s_barrier
	s_add_i32 s54, s54, 2
	s_add_u32 s34, s34, 0x100
	s_addc_u32 s35, s35, 0
	s_add_u32 s52, s52, 0x100
	s_addc_u32 s53, s53, 0
	s_cmp_gt_u32 s54, 13
	s_cbranch_scc0 .LBB0_301
	s_and_b64 vcc, exec, s[20:21]
	s_cbranch_vccz .LBB0_304
	s_barrier

; #define PG8_STAGE(bufoff, gbase, voff) do { _Pragma("unroll") for (int _i = 0; _i < 2; ++_i) \
;         __builtin_amdgcn_global_load_lds((const unsigned*)((const char*)(gbase) + (voff)[_i]), (PG8_LAS unsigned*)(lds + (bufoff) + ldsw + _i * 8192), 16, 0, 0); } while (0)
; #define PG8_LDA(dst, b, h) do { _Pragma("unroll") for (int m = 0; m < 4; ++m) _Pragma("unroll") for (int k = 0; k < 2; ++k) dst[m][k] = *(const PG8_LAS bf16x8*)(lds + PG8_SA(b, h) + aoff + m * 2048 + k * 1024); } while (0)
; #define PG8_LDB(dst, b, h) do { _Pragma("unroll") for (int n = 0; n < 2; ++n) _Pragma("unroll") for (int k = 0; k < 2; ++k) dst[n][k] = *(const PG8_LAS bf16x8*)(lds + PG8_SB(b, h) + boff + n * 2048 + k * 1024); } while (0)
; #define PG8_MMA(ai, bj, At, Bt) do { __builtin_amdgcn_s_setprio(1); _Pragma("unroll") for (int m = 0; m < 4; ++m) _Pragma("unroll") for (int n = 0; n < 2; ++n) _Pragma("unroll") for (int k = 0; k < 2; ++k) \
;         acc[ai][bj][m][n] = __builtin_amdgcn_mfma_f32_16x16x32_bf16(Bt[n][k], At[m][k], acc[ai][bj][m][n], 0, 0, 0); __builtin_amdgcn_s_setprio(0); } while (0)
; #define PG8_WAIT_V(n) asm volatile("s_waitcnt vmcnt(" #n ")" ::: "memory")
; #define PG8_BAR __builtin_amdgcn_s_barrier()
; template <class Epi, class Sched, bool ALIGN_EPI = false, bool SP2 = false>
; __device__ __forceinline__ void gemm_phase(PG8_LAS unsigned char* lds, const Gemm g, const Sched& S, const Epi& E, const int wave_s) {
;     ...
;         const char* nA = has_next ? (const char*)g.A + (size_t)nxt.pm * tstep + (size_t)nxt.k0 * kstep : cA; const char* nB = has_next ? (const char*)g.Bt + (size_t)nxt.pn * tstep + (size_t)nxt.k0 * kstep : cB;
;         const int clen = cur.len;
;         for (int t = 0; t < clen; t += 2) {
;             const bool last = (t == clen - 2);
;             const char* a1 = cA + (size_t)(t + 1) * kstep;
;             const char* a2 = last ? nA : cA + (size_t)(t + 2) * kstep; const char* b2 = last ? nB : cB + (size_t)(t + 2) * kstep;
;             const char* a3 = a2 + kstep; const char* b3 = b2 + kstep;
;             if (last && has_next) S.a_ready(nxt);
;             if constexpr (SP2) {
;             PG8_LDB(B0, 0, 0); PG8_LDB(B1, 0, 1); PG8_SCHED; PG8_LDA(At, 0, 0); PG8_STAGE(PG8_SA(1, 1), a1 + hstep, voffA);
;             PG8_WAIT_V(8); PG8_WAIT_L(0); PG8_BAR; PG8_MMA(0, 0, At, B0); PG8_MMA(0, 1, At, B1); PG8_BAR; PG8_SCHED;
.LBB0_522:
	s_ashr_i32 s19, s18, 31
	s_lshl_b64 s[20:21], s[18:19], 19
	s_add_u32 s20, s28, s20
	s_addc_u32 s21, s29, s21
	s_and_b64 s[22:23], s[6:7], exec
	s_cselect_b32 s19, s21, s25
	s_cselect_b32 s46, s20, s24
	s_ashr_i32 s17, s16, 31
	s_lshl_b64 s[22:23], s[16:17], 19
	s_add_u32 s22, s30, s22
	s_addc_u32 s23, s31, s23
	s_and_b64 s[26:27], s[6:7], exec
	s_cselect_b32 s17, s23, s3
	s_cselect_b32 s47, s22, s2
	s_add_u32 s24, s24, 0x40080
	s_addc_u32 s25, s25, 0
	s_add_u32 s48, s2, 0x100
	s_addc_u32 s49, s3, 0
	s_mov_b32 s50, -2
	s_add_u32 s2, s24, 0xfffc0080
	s_addc_u32 s3, s25, -1
	s_add_i32 s51, 0, 0x10000
	s_cmp_eq_u32 s50, 12
	s_cselect_b32 s27, s19, s3
	s_cselect_b32 s26, s46, s2
	v_add_u32_e32 v144, s51, v147
	s_cselect_b32 s3, s17, s49
	s_cselect_b32 s2, s47, s48
	s_add_i32 s54, 0, 0x14000
	ds_read_b128 v[140:143], v144
	ds_read_b128 v[150:153], v144 offset:1024
	ds_read_b128 v[154:157], v144 offset:2048
	ds_read_b128 v[158:161], v144 offset:3072
	v_add_u32_e32 v144, s54, v147
	ds_read_b128 v[174:177], v144
	ds_read_b128 v[178:181], v144 offset:1024
	ds_read_b128 v[182:185], v144 offset:2048
	ds_read_b128 v[186:189], v144 offset:3072
	v_lshl_add_u64 v[194:195], s[24:25], 0, v[136:137]
	s_add_i32 m0, s35, 0xc000
	ds_read_b128 v[190:193], v148
	ds_read_b128 v[210:213], v148 offset:1024
	ds_read_b128 v[214:217], v148 offset:2048
	ds_read_b128 v[218:221], v148 offset:3072
	ds_read_b128 v[222:225], v148 offset:4096
	ds_read_b128 v[226:229], v148 offset:5120
	ds_read_b128 v[230:233], v148 offset:6144
	ds_read_b128 v[234:237], v148 offset:7168
	global_load_lds_dwordx4 v[194:195], off
	v_lshl_add_u64 v[194:195], s[24:25], 0, v[138:139]
	s_add_i32 m0, s35, 0xe000
	s_nop 0
	global_load_lds_dwordx4 v[194:195], off
	s_waitcnt vmcnt(8)
	s_waitcnt lgkmcnt(0)
	s_barrier
	s_setprio 1
	s_waitcnt lgkmcnt(0)
	v_mfma_f32_16x16x32_bf16 v[124:127], v[140:143], v[190:193], 0
	v_mfma_f32_16x16x32_bf16 v[116:119], v[154:157], v[190:193], 0
	v_mfma_f32_16x16x32_bf16 v[108:111], v[140:143], v[214:217], 0
	v_mfma_f32_16x16x32_bf16 v[100:103], v[154:157], v[214:217], 0
	v_mfma_f32_16x16x32_bf16 v[92:95], v[140:143], v[222:225], 0
	v_mfma_f32_16x16x32_bf16 v[84:87], v[154:157], v[222:225], 0
	v_mfma_f32_16x16x32_bf16 v[76:79], v[140:143], v[230:233], 0
	v_mfma_f32_16x16x32_bf16 v[68:71], v[154:157], v[230:233], 0
	v_mfma_f32_16x16x32_bf16 v[124:127], v[150:153], v[210:213], v[124:127]
	v_mfma_f32_16x16x32_bf16 v[116:119], v[158:161], v[210:213], v[116:119]
	v_mfma_f32_16x16x32_bf16 v[108:111], v[150:153], v[218:221], v[108:111]
	v_mfma_f32_16x16x32_bf16 v[100:103], v[158:161], v[218:221], v[100:103]
	v_mfma_f32_16x16x32_bf16 v[92:95], v[150:153], v[226:229], v[92:95]
	v_mfma_f32_16x16x32_bf16 v[84:87], v[158:161], v[226:229], v[84:87]
	v_mfma_f32_16x16x32_bf16 v[76:79], v[150:153], v[234:237], v[76:79]
	v_mfma_f32_16x16x32_bf16 v[68:71], v[158:161], v[234:237], v[68:71]
	s_setprio 0
	s_setprio 1
	v_mfma_f32_16x16x32_bf16 v[120:123], v[174:177], v[190:193], 0
	v_mfma_f32_16x16x32_bf16 v[112:115], v[182:185], v[190:193], 0
	v_mfma_f32_16x16x32_bf16 v[104:107], v[174:177], v[214:217], 0
	v_mfma_f32_16x16x32_bf16 v[96:99], v[182:185], v[214:217], 0
	v_mfma_f32_16x16x32_bf16 v[88:91], v[174:177], v[222:225], 0
	v_mfma_f32_16x16x32_bf16 v[80:83], v[182:185], v[222:225], 0
	v_mfma_f32_16x16x32_bf16 v[72:75], v[174:177], v[230:233], 0
	v_mfma_f32_16x16x32_bf16 v[64:67], v[182:185], v[230:233], 0
	v_mfma_f32_16x16x32_bf16 v[120:123], v[178:181], v[210:213], v[120:123]
	v_mfma_f32_16x16x32_bf16 v[112:115], v[186:189], v[210:213], v[112:115]
	v_mfma_f32_16x16x32_bf16 v[104:107], v[178:181], v[218:221], v[104:107]
	v_mfma_f32_16x16x32_bf16 v[96:99], v[186:189], v[218:221], v[96:99]
	v_mfma_f32_16x16x32_bf16 v[88:91], v[178:181], v[226:229], v[88:91]
	v_mfma_f32_16x16x32_bf16 v[80:83], v[186:189], v[226:229], v[80:83]
	v_mfma_f32_16x16x32_bf16 v[72:75], v[178:181], v[234:237], v[72:75]
	v_mfma_f32_16x16x32_bf16 v[64:67], v[186:189], v[234:237], v[64:67]
	s_setprio 0
	s_barrier
; #define PG8_STAGE(bufoff, gbase, voff) do { _Pragma("unroll") for (int _i = 0; _i < 2; ++_i) \
;         __builtin_amdgcn_global_load_lds((const unsigned*)((const char*)(gbase) + (voff)[_i]), (PG8_LAS unsigned*)(lds + (bufoff) + ldsw + _i * 8192), 16, 0, 0); } while (0)
; #define PG8_LDA(dst, b, h) do { _Pragma("unroll") for (int m = 0; m < 4; ++m) _Pragma("unroll") for (int k = 0; k < 2; ++k) dst[m][k] = *(const PG8_LAS bf16x8*)(lds + PG8_SA(b, h) + aoff + m * 2048 + k * 1024); } while (0)
; #define PG8_MMA(ai, bj, At, Bt) do { __builtin_amdgcn_s_setprio(1); _Pragma("unroll") for (int m = 0; m < 4; ++m) _Pragma("unroll") for (int n = 0; n < 2; ++n) _Pragma("unroll") for (int k = 0; k < 2; ++k) \
;         acc[ai][bj][m][n] = __builtin_amdgcn_mfma_f32_16x16x32_bf16(Bt[n][k], At[m][k], acc[ai][bj][m][n], 0, 0, 0); __builtin_amdgcn_s_setprio(0); } while (0)
; #define PG8_WAIT_V(n) asm volatile("s_waitcnt vmcnt(" #n ")" ::: "memory")
; #define PG8_WAIT_L(n) asm volatile("s_waitcnt lgkmcnt(" #n ")" ::: "memory")
; #define PG8_BAR __builtin_amdgcn_s_barrier()
; #define PG8_SCHED __builtin_amdgcn_sched_barrier(0)
; template <class Epi, class Sched, bool ALIGN_EPI = false, bool SP2 = false>
; __device__ __forceinline__ void gemm_phase(PG8_LAS unsigned char* lds, const Gemm g, const Sched& S, const Epi& E, const int wave_s) {
;     ...
;             PG8_LDA(At, 0, 1); PG8_STAGE(PG8_SB(0, 0), b2, voffB); PG8_STAGE(PG8_SB(0, 1), b2 + hstep, voffB); PG8_STAGE(PG8_SA(0, 0), a2, voffA);
;             PG8_WAIT_V(8); PG8_WAIT_L(0); PG8_BAR; PG8_MMA(1, 0, At, B0); PG8_MMA(1, 1, At, B1); PG8_BAR; PG8_SCHED;
	s_add_i32 s51, s51, s34
	v_lshl_add_u64 v[194:195], s[2:3], 0, v[128:129]
	s_mov_b32 m0, s51
	ds_read_b128 v[190:193], v148 offset:16384
	ds_read_b128 v[210:213], v148 offset:17408
	ds_read_b128 v[214:217], v148 offset:18432
	ds_read_b128 v[218:221], v148 offset:19456
	ds_read_b128 v[222:225], v148 offset:20480
	ds_read_b128 v[226:229], v148 offset:21504
	ds_read_b128 v[230:233], v148 offset:22528
	ds_read_b128 v[234:237], v148 offset:23552
	global_load_lds_dwordx4 v[194:195], off
	s_add_i32 m0, s51, 0x2000
	s_add_u32 s52, s2, 0x40000
	v_lshl_add_u64 v[238:239], s[2:3], 0, v[130:131]
	s_addc_u32 s53, s3, 0
	s_add_i32 s51, s54, s34
	global_load_lds_dwordx4 v[238:239], off
	v_lshl_add_u64 v[240:241], s[52:53], 0, v[128:129]
	s_mov_b32 m0, s51
	v_lshl_add_u64 v[242:243], s[26:27], 0, v[132:133]
	global_load_lds_dwordx4 v[240:241], off
	v_lshl_add_u64 v[240:241], s[52:53], 0, v[130:131]
	s_add_i32 m0, s51, 0x2000
	s_nop 0
	global_load_lds_dwordx4 v[240:241], off
	v_lshl_add_u64 v[240:241], s[26:27], 0, v[134:135]
	s_mov_b32 m0, s35
	s_nop 0
	global_load_lds_dwordx4 v[240:241], off
	s_mov_b32 m0, s36
	s_nop 0
	global_load_lds_dwordx4 v[242:243], off
	s_waitcnt vmcnt(8)
	s_waitcnt lgkmcnt(0)
	s_barrier
	s_setprio 1
	s_waitcnt lgkmcnt(0)
	v_mfma_f32_16x16x32_bf16 v[60:63], v[140:143], v[190:193], 0
	v_mfma_f32_16x16x32_bf16 v[52:55], v[154:157], v[190:193], 0
	v_mfma_f32_16x16x32_bf16 v[44:47], v[140:143], v[214:217], 0
	v_mfma_f32_16x16x32_bf16 v[36:39], v[154:157], v[214:217], 0
	v_mfma_f32_16x16x32_bf16 v[28:31], v[140:143], v[222:225], 0
	v_mfma_f32_16x16x32_bf16 v[20:23], v[154:157], v[222:225], 0
	v_mfma_f32_16x16x32_bf16 v[12:15], v[140:143], v[230:233], 0
	v_mfma_f32_16x16x32_bf16 v[4:7], v[154:157], v[230:233], 0
	v_mfma_f32_16x16x32_bf16 v[60:63], v[150:153], v[210:213], v[60:63]
	v_mfma_f32_16x16x32_bf16 v[52:55], v[158:161], v[210:213], v[52:55]
	v_mfma_f32_16x16x32_bf16 v[44:47], v[150:153], v[218:221], v[44:47]
	v_mfma_f32_16x16x32_bf16 v[36:39], v[158:161], v[218:221], v[36:39]
	v_mfma_f32_16x16x32_bf16 v[28:31], v[150:153], v[226:229], v[28:31]
	v_mfma_f32_16x16x32_bf16 v[20:23], v[158:161], v[226:229], v[20:23]
	v_mfma_f32_16x16x32_bf16 v[12:15], v[150:153], v[234:237], v[12:15]
	v_mfma_f32_16x16x32_bf16 v[4:7], v[158:161], v[234:237], v[4:7]
	s_setprio 0
	s_setprio 1
	v_mfma_f32_16x16x32_bf16 v[56:59], v[174:177], v[190:193], 0
	v_mfma_f32_16x16x32_bf16 v[48:51], v[182:185], v[190:193], 0
	v_mfma_f32_16x16x32_bf16 v[40:43], v[174:177], v[214:217], 0
	v_mfma_f32_16x16x32_bf16 v[32:35], v[182:185], v[214:217], 0
	v_mfma_f32_16x16x32_bf16 v[24:27], v[174:177], v[222:225], 0
	v_mfma_f32_16x16x32_bf16 v[16:19], v[182:185], v[222:225], 0
	v_mfma_f32_16x16x32_bf16 v[8:11], v[174:177], v[230:233], 0
	v_mfma_f32_16x16x32_bf16 v[0:3], v[182:185], v[230:233], 0
	v_mfma_f32_16x16x32_bf16 v[56:59], v[178:181], v[210:213], v[56:59]
	v_mfma_f32_16x16x32_bf16 v[48:51], v[186:189], v[210:213], v[48:51]
	v_mfma_f32_16x16x32_bf16 v[40:43], v[178:181], v[218:221], v[40:43]
	v_mfma_f32_16x16x32_bf16 v[32:35], v[186:189], v[218:221], v[32:35]
	v_mfma_f32_16x16x32_bf16 v[24:27], v[178:181], v[226:229], v[24:27]
	v_mfma_f32_16x16x32_bf16 v[16:19], v[186:189], v[226:229], v[16:19]
	v_mfma_f32_16x16x32_bf16 v[8:11], v[178:181], v[234:237], v[8:11]
	v_mfma_f32_16x16x32_bf16 v[0:3], v[186:189], v[234:237], v[0:3]
	s_setprio 0
	s_barrier
	s_branch .Lpeel1_seg3

; #define PG8_STAGE(bufoff, gbase, voff) do { _Pragma("unroll") for (int _i = 0; _i < 2; ++_i) \
;         __builtin_amdgcn_global_load_lds((const unsigned*)((const char*)(gbase) + (voff)[_i]), (PG8_LAS unsigned*)(lds + (bufoff) + ldsw + _i * 8192), 16, 0, 0); } while (0)
; #define PG8_LDA(dst, b, h) do { _Pragma("unroll") for (int m = 0; m < 4; ++m) _Pragma("unroll") for (int k = 0; k < 2; ++k) dst[m][k] = *(const PG8_LAS bf16x8*)(lds + PG8_SA(b, h) + aoff + m * 2048 + k * 1024); } while (0)
; #define PG8_LDB(dst, b, h) do { _Pragma("unroll") for (int n = 0; n < 2; ++n) _Pragma("unroll") for (int k = 0; k < 2; ++k) dst[n][k] = *(const PG8_LAS bf16x8*)(lds + PG8_SB(b, h) + boff + n * 2048 + k * 1024); } while (0)
; #define PG8_MMA(ai, bj, At, Bt) do { __builtin_amdgcn_s_setprio(1); _Pragma("unroll") for (int m = 0; m < 4; ++m) _Pragma("unroll") for (int n = 0; n < 2; ++n) _Pragma("unroll") for (int k = 0; k < 2; ++k) \
;         acc[ai][bj][m][n] = __builtin_amdgcn_mfma_f32_16x16x32_bf16(Bt[n][k], At[m][k], acc[ai][bj][m][n], 0, 0, 0); __builtin_amdgcn_s_setprio(0); } while (0)
; #define PG8_WAIT_V(n) asm volatile("s_waitcnt vmcnt(" #n ")" ::: "memory")
; #define PG8_WAIT_L(n) asm volatile("s_waitcnt lgkmcnt(" #n ")" ::: "memory")
; #define PG8_BAR __builtin_amdgcn_s_barrier()
; #define PG8_SCHED __builtin_amdgcn_sched_barrier(0)
; template <class Epi, class Sched, bool ALIGN_EPI = false, bool SP2 = false>
; __device__ __forceinline__ void gemm_phase(PG8_LAS unsigned char* lds, const Gemm g, const Sched& S, const Epi& E, const int wave_s) {
;     ...
;             PG8_LDB(B0, 1, 0); PG8_LDB(B1, 1, 1); PG8_SCHED; PG8_LDA(At, 1, 0); PG8_STAGE(PG8_SA(0, 1), a2 + hstep, voffA);
;             PG8_WAIT_V(8); PG8_WAIT_L(0); PG8_BAR; PG8_MMA(0, 0, At, B0); PG8_MMA(0, 1, At, B1); PG8_BAR; PG8_SCHED;
.Lpeel1_seg3:
	s_add_i32 s51, 0, 0x18000
	v_add_u32_e32 v144, s51, v147
	s_add_i32 s52, 0, 0x1c000
	ds_read_b128 v[140:143], v144
	ds_read_b128 v[150:153], v144 offset:1024
	ds_read_b128 v[154:157], v144 offset:2048
	ds_read_b128 v[158:161], v144 offset:3072
	v_add_u32_e32 v144, s52, v147
	ds_read_b128 v[174:177], v144
	ds_read_b128 v[178:181], v144 offset:1024
	ds_read_b128 v[182:185], v144 offset:2048
	ds_read_b128 v[186:189], v144 offset:3072
	s_add_u32 s26, s26, 0x40000
	s_addc_u32 s27, s27, 0
	s_mov_b32 m0, s37
	v_lshl_add_u64 v[244:245], s[26:27], 0, v[134:135]
	ds_read_b128 v[190:193], v148 offset:32768
	ds_read_b128 v[210:213], v148 offset:33792
	ds_read_b128 v[214:217], v148 offset:34816
	ds_read_b128 v[218:221], v148 offset:35840
	ds_read_b128 v[222:225], v148 offset:36864
	ds_read_b128 v[226:229], v148 offset:37888
	ds_read_b128 v[230:233], v148 offset:38912
	ds_read_b128 v[234:237], v148 offset:39936
	global_load_lds_dwordx4 v[244:245], off
	v_lshl_add_u64 v[244:245], s[26:27], 0, v[132:133]
	s_mov_b32 m0, s38
	s_nop 0
	global_load_lds_dwordx4 v[244:245], off
	s_waitcnt vmcnt(8)
	s_waitcnt lgkmcnt(0)
	s_barrier
	s_setprio 1
	s_waitcnt lgkmcnt(0)
	v_mfma_f32_16x16x32_bf16 v[124:127], v[140:143], v[190:193], v[124:127]
	v_mfma_f32_16x16x32_bf16 v[116:119], v[154:157], v[190:193], v[116:119]
	v_mfma_f32_16x16x32_bf16 v[108:111], v[140:143], v[214:217], v[108:111]
	v_mfma_f32_16x16x32_bf16 v[100:103], v[154:157], v[214:217], v[100:103]
	v_mfma_f32_16x16x32_bf16 v[92:95], v[140:143], v[222:225], v[92:95]
	v_mfma_f32_16x16x32_bf16 v[84:87], v[154:157], v[222:225], v[84:87]
	v_mfma_f32_16x16x32_bf16 v[76:79], v[140:143], v[230:233], v[76:79]
	v_mfma_f32_16x16x32_bf16 v[68:71], v[154:157], v[230:233], v[68:71]
	v_mfma_f32_16x16x32_bf16 v[124:127], v[150:153], v[210:213], v[124:127]
	v_mfma_f32_16x16x32_bf16 v[116:119], v[158:161], v[210:213], v[116:119]
	v_mfma_f32_16x16x32_bf16 v[108:111], v[150:153], v[218:221], v[108:111]
	v_mfma_f32_16x16x32_bf16 v[100:103], v[158:161], v[218:221], v[100:103]
	v_mfma_f32_16x16x32_bf16 v[92:95], v[150:153], v[226:229], v[92:95]
	v_mfma_f32_16x16x32_bf16 v[84:87], v[158:161], v[226:229], v[84:87]
	v_mfma_f32_16x16x32_bf16 v[76:79], v[150:153], v[234:237], v[76:79]
	v_mfma_f32_16x16x32_bf16 v[68:71], v[158:161], v[234:237], v[68:71]
	s_setprio 0
	s_setprio 1
	v_mfma_f32_16x16x32_bf16 v[120:123], v[174:177], v[190:193], v[120:123]
	v_mfma_f32_16x16x32_bf16 v[112:115], v[182:185], v[190:193], v[112:115]
	v_mfma_f32_16x16x32_bf16 v[104:107], v[174:177], v[214:217], v[104:107]
	v_mfma_f32_16x16x32_bf16 v[96:99], v[182:185], v[214:217], v[96:99]
	v_mfma_f32_16x16x32_bf16 v[88:91], v[174:177], v[222:225], v[88:91]
	v_mfma_f32_16x16x32_bf16 v[80:83], v[182:185], v[222:225], v[80:83]
	v_mfma_f32_16x16x32_bf16 v[72:75], v[174:177], v[230:233], v[72:75]
	v_mfma_f32_16x16x32_bf16 v[64:67], v[182:185], v[230:233], v[64:67]
	v_mfma_f32_16x16x32_bf16 v[120:123], v[178:181], v[210:213], v[120:123]
	v_mfma_f32_16x16x32_bf16 v[112:115], v[186:189], v[210:213], v[112:115]
	v_mfma_f32_16x16x32_bf16 v[104:107], v[178:181], v[218:221], v[104:107]
	v_mfma_f32_16x16x32_bf16 v[96:99], v[186:189], v[218:221], v[96:99]
	v_mfma_f32_16x16x32_bf16 v[88:91], v[178:181], v[226:229], v[88:91]
	v_mfma_f32_16x16x32_bf16 v[80:83], v[186:189], v[226:229], v[80:83]
	v_mfma_f32_16x16x32_bf16 v[72:75], v[178:181], v[234:237], v[72:75]
	v_mfma_f32_16x16x32_bf16 v[64:67], v[186:189], v[234:237], v[64:67]
	s_setprio 0
	s_barrier
; #define PG8_STAGE(bufoff, gbase, voff) do { _Pragma("unroll") for (int _i = 0; _i < 2; ++_i) \
;         __builtin_amdgcn_global_load_lds((const unsigned*)((const char*)(gbase) + (voff)[_i]), (PG8_LAS unsigned*)(lds + (bufoff) + ldsw + _i * 8192), 16, 0, 0); } while (0)
; #define PG8_LDA(dst, b, h) do { _Pragma("unroll") for (int m = 0; m < 4; ++m) _Pragma("unroll") for (int k = 0; k < 2; ++k) dst[m][k] = *(const PG8_LAS bf16x8*)(lds + PG8_SA(b, h) + aoff + m * 2048 + k * 1024); } while (0)
; #define PG8_MMA(ai, bj, At, Bt) do { __builtin_amdgcn_s_setprio(1); _Pragma("unroll") for (int m = 0; m < 4; ++m) _Pragma("unroll") for (int n = 0; n < 2; ++n) _Pragma("unroll") for (int k = 0; k < 2; ++k) \
;         acc[ai][bj][m][n] = __builtin_amdgcn_mfma_f32_16x16x32_bf16(Bt[n][k], At[m][k], acc[ai][bj][m][n], 0, 0, 0); __builtin_amdgcn_s_setprio(0); } while (0)
; #define PG8_WAIT_V(n) asm volatile("s_waitcnt vmcnt(" #n ")" ::: "memory")
; #define PG8_WAIT_L(n) asm volatile("s_waitcnt lgkmcnt(" #n ")" ::: "memory")
; #define PG8_BAR __builtin_amdgcn_s_barrier()
; #define PG8_SCHED __builtin_amdgcn_sched_barrier(0)
; template <class Epi, class Sched, bool ALIGN_EPI = false, bool SP2 = false>
; __device__ __forceinline__ void gemm_phase(PG8_LAS unsigned char* lds, const Gemm g, const Sched& S, const Epi& E, const int wave_s) {
;     ...
;         for (int t = 0; t < clen; t += 2) {
;     ...
;             PG8_LDA(At, 1, 1); PG8_STAGE(PG8_SB(1, 0), b3, voffB); PG8_STAGE(PG8_SB(1, 1), b3 + hstep, voffB); PG8_STAGE(PG8_SA(1, 0), a3, voffA);
;             PG8_WAIT_V(8); PG8_WAIT_L(0); PG8_BAR; PG8_MMA(1, 0, At, B0); PG8_MMA(1, 1, At, B1); PG8_BAR; PG8_SCHED;
	s_add_i32 s26, s51, s34
	v_lshl_add_u64 v[194:195], v[194:195], 0, s[4:5]
	s_mov_b32 m0, s26
	ds_read_b128 v[190:193], v148 offset:49152
	ds_read_b128 v[210:213], v148 offset:50176
	ds_read_b128 v[214:217], v148 offset:51200
	ds_read_b128 v[218:221], v148 offset:52224
	ds_read_b128 v[222:225], v148 offset:53248
	ds_read_b128 v[226:229], v148 offset:54272
	ds_read_b128 v[230:233], v148 offset:55296
	ds_read_b128 v[234:237], v148 offset:56320
	global_load_lds_dwordx4 v[194:195], off
	s_add_i32 m0, s26, 0x2000
	s_add_u32 s2, s2, 0x40080
	v_lshl_add_u64 v[194:195], v[238:239], 0, s[4:5]
	s_addc_u32 s3, s3, 0
	s_add_i32 s26, s52, s34
	global_load_lds_dwordx4 v[194:195], off
	v_lshl_add_u64 v[194:195], s[2:3], 0, v[128:129]
	s_mov_b32 m0, s26
	s_nop 0
	global_load_lds_dwordx4 v[194:195], off
	v_lshl_add_u64 v[194:195], s[2:3], 0, v[130:131]
	s_add_i32 m0, s26, 0x2000
	s_nop 0
	global_load_lds_dwordx4 v[194:195], off
	v_lshl_add_u64 v[194:195], v[240:241], 0, s[4:5]
	s_mov_b32 m0, s41
	s_nop 0
	global_load_lds_dwordx4 v[194:195], off
	v_lshl_add_u64 v[194:195], v[242:243], 0, s[4:5]
	s_mov_b32 m0, s42
	s_nop 0
	global_load_lds_dwordx4 v[194:195], off
	s_waitcnt vmcnt(8)
	s_waitcnt lgkmcnt(0)
	s_barrier
	s_setprio 1
	s_waitcnt lgkmcnt(0)
	v_mfma_f32_16x16x32_bf16 v[60:63], v[140:143], v[190:193], v[60:63]
	v_mfma_f32_16x16x32_bf16 v[52:55], v[154:157], v[190:193], v[52:55]
	v_mfma_f32_16x16x32_bf16 v[44:47], v[140:143], v[214:217], v[44:47]
	v_mfma_f32_16x16x32_bf16 v[36:39], v[154:157], v[214:217], v[36:39]
	v_mfma_f32_16x16x32_bf16 v[28:31], v[140:143], v[222:225], v[28:31]
	v_mfma_f32_16x16x32_bf16 v[20:23], v[154:157], v[222:225], v[20:23]
	v_mfma_f32_16x16x32_bf16 v[12:15], v[140:143], v[230:233], v[12:15]
	v_mfma_f32_16x16x32_bf16 v[4:7], v[154:157], v[230:233], v[4:7]
	v_mfma_f32_16x16x32_bf16 v[60:63], v[150:153], v[210:213], v[60:63]
	v_mfma_f32_16x16x32_bf16 v[52:55], v[158:161], v[210:213], v[52:55]
	v_mfma_f32_16x16x32_bf16 v[44:47], v[150:153], v[218:221], v[44:47]
	v_mfma_f32_16x16x32_bf16 v[36:39], v[158:161], v[218:221], v[36:39]
	v_mfma_f32_16x16x32_bf16 v[28:31], v[150:153], v[226:229], v[28:31]
	v_mfma_f32_16x16x32_bf16 v[20:23], v[158:161], v[226:229], v[20:23]
	v_mfma_f32_16x16x32_bf16 v[12:15], v[150:153], v[234:237], v[12:15]
	v_mfma_f32_16x16x32_bf16 v[4:7], v[158:161], v[234:237], v[4:7]
	s_setprio 0
	s_setprio 1
	v_mfma_f32_16x16x32_bf16 v[56:59], v[174:177], v[190:193], v[56:59]
	v_mfma_f32_16x16x32_bf16 v[48:51], v[182:185], v[190:193], v[48:51]
	v_mfma_f32_16x16x32_bf16 v[40:43], v[174:177], v[214:217], v[40:43]
	v_mfma_f32_16x16x32_bf16 v[32:35], v[182:185], v[214:217], v[32:35]
	v_mfma_f32_16x16x32_bf16 v[24:27], v[174:177], v[222:225], v[24:27]
	v_mfma_f32_16x16x32_bf16 v[16:19], v[182:185], v[222:225], v[16:19]
	v_mfma_f32_16x16x32_bf16 v[8:11], v[174:177], v[230:233], v[8:11]
	v_mfma_f32_16x16x32_bf16 v[0:3], v[182:185], v[230:233], v[0:3]
	v_mfma_f32_16x16x32_bf16 v[56:59], v[178:181], v[210:213], v[56:59]
	v_mfma_f32_16x16x32_bf16 v[48:51], v[186:189], v[210:213], v[48:51]
	v_mfma_f32_16x16x32_bf16 v[40:43], v[178:181], v[218:221], v[40:43]
	v_mfma_f32_16x16x32_bf16 v[32:35], v[186:189], v[218:221], v[32:35]
	v_mfma_f32_16x16x32_bf16 v[24:27], v[178:181], v[226:229], v[24:27]
	v_mfma_f32_16x16x32_bf16 v[16:19], v[186:189], v[226:229], v[16:19]
	v_mfma_f32_16x16x32_bf16 v[8:11], v[178:181], v[234:237], v[8:11]
	v_mfma_f32_16x16x32_bf16 v[0:3], v[186:189], v[234:237], v[0:3]
	s_setprio 0
	s_barrier
	s_add_i32 s50, s50, 2
	s_add_u32 s24, s24, 0x100
	s_addc_u32 s25, s25, 0
	s_add_u32 s48, s48, 0x100
	s_addc_u32 s49, s49, 0
	s_cmp_gt_u32 s50, 13
	s_cbranch_scc0 .LBB0_523
	s_and_b64 vcc, exec, s[14:15]
	s_cbranch_vccz .LBB0_526
	s_barrier
